# SWA inner loop: all eight K-tile LDS reads of the QK product issued up front into free VGPRs with counted lgkmcnt waits (was: read pair, wait, MFMA pair, three times)
# baseline (speedup 1.0000x reference)
.LBB0_576:
	s_lshl_b32 s78, s14, 13
	s_lshl_b32 s14, s14, 6
	s_or_b32 s14, s76, s14
	s_sub_i32 s16, s45, s14
	s_or_b32 s17, s16, 30
	s_cmpk_lt_u32 s17, 0xde
	s_cselect_b64 s[14:15], -1, 0
	s_cmpk_gt_u32 s17, 0xdd
	s_cbranch_scc1 .LBB0_582
	v_add_u32_e32 v0, s78, v131
	s_setprio 1
	v_add_u32_e32 v38, v0, v121
	ds_read_b128 v[34:37], v38
	ds_read_b128 v[50:53], v38 offset:4096
	v_add_u32_e32 v99, v0, v122
	ds_read_b128 v[132:135], v99
	ds_read_b128 v[136:139], v99 offset:4096
	v_add_u32_e32 v99, v0, v123
	ds_read_b128 v[148:151], v99
	ds_read_b128 v[152:155], v99 offset:4096
	v_add_u32_e32 v0, v0, v124
	ds_read_b128 v[156:159], v0
	ds_read_b128 v[160:163], v0 offset:4096
	s_waitcnt lgkmcnt(7)
	v_mfma_f32_32x32x16_bf16 v[34:49], v[34:37], v[66:69], 0
	s_waitcnt lgkmcnt(6)
	v_mfma_f32_32x32x16_bf16 v[50:65], v[50:53], v[66:69], 0
	s_waitcnt lgkmcnt(5)
	v_mfma_f32_32x32x16_bf16 v[34:49], v[132:135], v[70:73], v[34:49]
	s_waitcnt lgkmcnt(4)
	v_mfma_f32_32x32x16_bf16 v[50:65], v[136:139], v[70:73], v[50:65]
	s_waitcnt lgkmcnt(3)
	v_mfma_f32_32x32x16_bf16 v[34:49], v[148:151], v[74:77], v[34:49]
	s_waitcnt lgkmcnt(2)
	v_mfma_f32_32x32x16_bf16 v[50:65], v[152:155], v[74:77], v[50:65]
	s_waitcnt lgkmcnt(1)
	v_mfma_f32_32x32x16_bf16 v[34:49], v[156:159], v[78:81], v[34:49]
	s_waitcnt lgkmcnt(0)
	v_mfma_f32_32x32x16_bf16 v[50:65], v[160:163], v[78:81], v[50:65]
	s_setprio 0
	v_or_b32_e32 v134, s16, v119
	v_sub_u32_e32 v0, v134, v144
	v_add_u32_e32 v99, v134, v83
	v_sub_u32_e32 v143, v134, v85
	v_sub_u32_e32 v146, v134, v82
	v_sub_u32_e32 v141, v134, v87
	v_sub_u32_e32 v145, v134, v84
	v_sub_u32_e32 v139, v134, v89
	v_sub_u32_e32 v142, v134, v86
	v_sub_u32_e32 v137, v134, v91
	v_sub_u32_e32 v140, v134, v88
	v_sub_u32_e32 v135, v134, v93
	v_sub_u32_e32 v138, v134, v90
	v_sub_u32_e32 v133, v134, v95
	v_sub_u32_e32 v136, v134, v92
	v_sub_u32_e32 v132, v134, v97
	v_sub_u32_e32 v134, v134, v94
	v_cvt_f32_i32_e32 v149, v99
	v_cvt_f32_i32_e32 v148, v0
	v_cvt_f32_i32_e32 v151, v143
	v_cvt_f32_i32_e32 v150, v146
	v_cvt_f32_i32_e32 v153, v141
	v_cvt_f32_i32_e32 v152, v145
	v_cvt_f32_i32_e32 v155, v139
	v_cvt_f32_i32_e32 v154, v142
	v_cvt_f32_i32_e32 v157, v137
	v_cvt_f32_i32_e32 v156, v140
	v_cvt_f32_i32_e32 v159, v135
	v_cvt_f32_i32_e32 v158, v138
	v_cvt_f32_i32_e32 v161, v133
	v_cvt_f32_i32_e32 v160, v136
	v_cvt_f32_i32_e32 v163, v132
	v_cvt_f32_i32_e32 v162, v134
	s_xor_b32 s29, s74, 0x80000000
	s_xor_b32 s28, s73, 0x80000000
	s_xor_b32 s31, s72, 0x80000000
	s_xor_b32 s30, s71, 0x80000000
	s_xor_b32 s81, s70, 0x80000000
	s_xor_b32 s80, s69, 0x80000000
	s_xor_b32 s83, s68, 0x80000000
	s_xor_b32 s82, s67, 0x80000000
	s_xor_b32 s85, s66, 0x80000000
	s_xor_b32 s84, s65, 0x80000000
	s_xor_b32 s87, s64, 0x80000000
	s_xor_b32 s86, s63, 0x80000000
	s_xor_b32 s89, s62, 0x80000000
	s_xor_b32 s88, s51, 0x80000000
	v_pk_fma_f32 v[34:35], s[8:9], v[148:149], v[34:35] neg_lo:[1,0,0] neg_hi:[1,0,0]
	v_pk_fma_f32 v[48:49], s[28:29], v[162:163], v[48:49]
	v_pk_fma_f32 v[46:47], s[30:31], v[160:161], v[46:47]
	v_pk_fma_f32 v[44:45], s[80:81], v[158:159], v[44:45]
	v_pk_fma_f32 v[42:43], s[82:83], v[156:157], v[42:43]
	v_pk_fma_f32 v[40:41], s[84:85], v[154:155], v[40:41]
	v_pk_fma_f32 v[38:39], s[86:87], v[152:153], v[38:39]
	v_pk_fma_f32 v[36:37], s[88:89], v[150:151], v[36:37]
	v_pk_add_f32 v[148:149], v[148:149], s[4:5] op_sel_hi:[1,0]
	v_pk_add_f32 v[150:151], v[150:151], s[4:5] op_sel_hi:[1,0]
	v_pk_add_f32 v[152:153], v[152:153], s[4:5] op_sel_hi:[1,0]
	v_pk_add_f32 v[154:155], v[154:155], s[4:5] op_sel_hi:[1,0]
	v_pk_add_f32 v[156:157], v[156:157], s[4:5] op_sel_hi:[1,0]
	v_pk_add_f32 v[158:159], v[158:159], s[4:5] op_sel_hi:[1,0]
	v_pk_add_f32 v[160:161], v[160:161], s[4:5] op_sel_hi:[1,0]
	v_pk_add_f32 v[162:163], v[162:163], s[4:5] op_sel_hi:[1,0]
	s_addk_i32 s16, 0xff9f
	v_pk_fma_f32 v[50:51], s[8:9], v[148:149], v[50:51] neg_lo:[1,0,0] neg_hi:[1,0,0]
	v_pk_fma_f32 v[64:65], s[28:29], v[162:163], v[64:65]
	v_pk_fma_f32 v[62:63], s[30:31], v[160:161], v[62:63]
	v_pk_fma_f32 v[60:61], s[80:81], v[158:159], v[60:61]
	v_pk_fma_f32 v[58:59], s[82:83], v[156:157], v[58:59]
	v_pk_fma_f32 v[56:57], s[84:85], v[154:155], v[56:57]
	v_pk_fma_f32 v[54:55], s[86:87], v[152:153], v[54:55]
	s_cmp_gt_u32 s16, 0xffffffdd
	v_pk_fma_f32 v[52:53], s[88:89], v[150:151], v[52:53]
	s_cbranch_scc1 .LBB0_579
	v_cmp_gt_u32_e32 vcc, s40, v0
	v_add_u32_e32 v0, 0xffffff60, v0
	s_nop 0
	v_cndmask_b32_e32 v34, v128, v34, vcc
	v_cmp_lt_u32_e32 vcc, s41, v0
	v_add_u32_e32 v0, 0xffffff60, v99
	s_nop 0
	v_cndmask_b32_e32 v50, v128, v50, vcc
	v_cmp_gt_u32_e32 vcc, s40, v99
	s_nop 1
	v_cndmask_b32_e32 v35, v128, v35, vcc
	v_cmp_lt_u32_e32 vcc, s41, v0
	v_add_u32_e32 v0, 0xffffff60, v146
	s_nop 0
	v_cndmask_b32_e32 v51, v128, v51, vcc
	v_cmp_gt_u32_e32 vcc, s40, v146
	s_nop 1
	v_cndmask_b32_e32 v36, v128, v36, vcc
	v_cmp_lt_u32_e32 vcc, s41, v0
	v_add_u32_e32 v0, 0xffffff60, v143
	s_nop 0
	v_cndmask_b32_e32 v52, v128, v52, vcc
	v_cmp_gt_u32_e32 vcc, s40, v143
	s_nop 1
	v_cndmask_b32_e32 v37, v128, v37, vcc
	v_cmp_lt_u32_e32 vcc, s41, v0
	v_add_u32_e32 v0, 0xffffff60, v145
	s_nop 0
	v_cndmask_b32_e32 v53, v128, v53, vcc
	v_cmp_gt_u32_e32 vcc, s40, v145
	s_nop 1
	v_cndmask_b32_e32 v38, v128, v38, vcc
	v_cmp_lt_u32_e32 vcc, s41, v0
	v_add_u32_e32 v0, 0xffffff60, v141
	s_nop 0
	v_cndmask_b32_e32 v54, v128, v54, vcc
	v_cmp_gt_u32_e32 vcc, s40, v141
	s_nop 1
	v_cndmask_b32_e32 v39, v128, v39, vcc
	v_cmp_lt_u32_e32 vcc, s41, v0
	v_add_u32_e32 v0, 0xffffff60, v142
	s_nop 0
	v_cndmask_b32_e32 v55, v128, v55, vcc
	v_cmp_gt_u32_e32 vcc, s40, v142
	s_nop 1
	v_cndmask_b32_e32 v40, v128, v40, vcc
	v_cmp_lt_u32_e32 vcc, s41, v0
	v_add_u32_e32 v0, 0xffffff60, v139
	s_nop 0
	v_cndmask_b32_e32 v56, v128, v56, vcc
	v_cmp_gt_u32_e32 vcc, s40, v139
	s_nop 1
	v_cndmask_b32_e32 v41, v128, v41, vcc
	v_cmp_lt_u32_e32 vcc, s41, v0
	v_add_u32_e32 v0, 0xffffff60, v140
	s_nop 0
	v_cndmask_b32_e32 v57, v128, v57, vcc
	v_cmp_gt_u32_e32 vcc, s40, v140
	s_nop 1
	v_cndmask_b32_e32 v42, v128, v42, vcc
	v_cmp_lt_u32_e32 vcc, s41, v0
	v_add_u32_e32 v0, 0xffffff60, v137
	s_nop 0
	v_cndmask_b32_e32 v58, v128, v58, vcc
	v_cmp_gt_u32_e32 vcc, s40, v137
	s_nop 1
	v_cndmask_b32_e32 v43, v128, v43, vcc
	v_cmp_lt_u32_e32 vcc, s41, v0
	v_add_u32_e32 v0, 0xffffff60, v138
	s_nop 0
	v_cndmask_b32_e32 v59, v128, v59, vcc
	v_cmp_gt_u32_e32 vcc, s40, v138
	s_nop 1
	v_cndmask_b32_e32 v44, v128, v44, vcc
	v_cmp_lt_u32_e32 vcc, s41, v0
	v_add_u32_e32 v0, 0xffffff60, v135
	s_nop 0
	v_cndmask_b32_e32 v60, v128, v60, vcc
	v_cmp_gt_u32_e32 vcc, s40, v135
	s_nop 1
	v_cndmask_b32_e32 v45, v128, v45, vcc
	v_cmp_lt_u32_e32 vcc, s41, v0
	v_add_u32_e32 v0, 0xffffff60, v136
	s_nop 0
	v_cndmask_b32_e32 v61, v128, v61, vcc
	v_cmp_gt_u32_e32 vcc, s40, v136
	s_nop 1
	v_cndmask_b32_e32 v46, v128, v46, vcc
	v_cmp_lt_u32_e32 vcc, s41, v0
	v_add_u32_e32 v0, 0xffffff60, v133
	s_nop 0
	v_cndmask_b32_e32 v62, v128, v62, vcc
	v_cmp_gt_u32_e32 vcc, s40, v133
	s_nop 1
	v_cndmask_b32_e32 v47, v128, v47, vcc
	v_cmp_lt_u32_e32 vcc, s41, v0
	v_add_u32_e32 v0, 0xffffff60, v134
	s_nop 0
	v_cndmask_b32_e32 v63, v128, v63, vcc
	v_cmp_gt_u32_e32 vcc, s40, v134
	s_nop 1
	v_cndmask_b32_e32 v48, v128, v48, vcc
	v_cmp_lt_u32_e32 vcc, s41, v0
	v_add_u32_e32 v0, 0xffffff60, v132
	s_nop 0
	v_cndmask_b32_e32 v64, v128, v64, vcc
	v_cmp_gt_u32_e32 vcc, s40, v132
	s_nop 1
	v_cndmask_b32_e32 v49, v128, v49, vcc
	v_cmp_lt_u32_e32 vcc, s41, v0
	s_nop 1
	v_cndmask_b32_e32 v65, v128, v65, vcc
